# MLA matrix block: first four K fragments of the next tile read during PV instead of after it
# speedup vs baseline: 1.0046x; 1.0046x over previous
; #define MLA_DMA(t, slot) do { _Pragma("unroll") for (int i_ = 0; i_ < 4; ++i_) { const bf16_t* src_ = (pisk[i_] ? kbase : vbase) + poff[i_] + (size_t)(t) * pstep[i_]; \
;         __builtin_amdgcn_global_load_lds((const unsigned*)src_, (LAS unsigned*)(lds + (slot) * SLOT + (w + 8 * i_) * 1024), 16, 0, 0); } } while (0)
; DI void mla_attn_phase(LAS unsigned char* lds, const bf16_t* Qg, const bf16_t* Kg, const bf16_t* Vtg, bf16_t* MIX) {
;     ...
;             const int qb = half ? pi : 63 - pi, q0 = qb * 256 + 32 * w, NT = 4 * (qb + 1);
;     ...
;             const bf16_t* qp = Qg + ((size_t)bh * SEQ + q0 + r32) * 96 + 8 * hf;
;             bf16x8 qf[6];
; #pragma unroll
;             for (int ks = 0; ks < 6; ++ks) qf[ks] = *(const bf16x8*)(qp + 16 * ks);
;             asm volatile("" ::: "memory");
;             MLA_DMA(0, 0); MLA_DMA(1, 1);
;             f32x16 o[4];
; #pragma unroll
;             for (int mt = 0; mt < 4; ++mt)
; #pragma unroll
;                 for (int i = 0; i < 16; ++i) o[mt][i] = 0.f;
;             float m_run = -1e30f, l_run = 0.f;
;     ...
;             asm volatile("s_waitcnt vmcnt(4)" ::: "memory");
;             __builtin_amdgcn_s_barrier(); asm volatile("" ::: "memory");
;             int sl = 0;
.LBB0_357:
	s_and_b64 s[26:27], s[24:25], exec
	s_cselect_b32 s8, s37, s36
	s_lshl_b32 s26, s8, 8
	s_add_i32 s26, s26, s34
	s_ashr_i32 s27, s26, 31
	v_lshl_add_u64 v[0:1], v[180:181], 0, s[26:27]
	s_movk_i32 s30, 0xc0
	s_waitcnt lgkmcnt(0)
	v_mad_u64_u32 v[4:5], s[28:29], v0, s30, v[168:169]
	v_mad_i32_i24 v5, v1, s30, v5
	s_mov_b32 m0, s35
	global_load_dwordx4 v[112:115], v[4:5], off
	global_load_dwordx4 v[116:119], v[4:5], off offset:32
	global_load_dwordx4 v[120:123], v[4:5], off offset:64
	global_load_dwordx4 v[124:127], v[4:5], off offset:96
	global_load_dwordx4 v[128:131], v[4:5], off offset:128
	global_load_dwordx4 v[132:135], v[4:5], off offset:160
	global_load_lds_dwordx4 v[184:185], off
	s_add_i32 m0, s35, 0x2000
	s_nop 0
	global_load_lds_dwordx4 v[186:187], off
	s_add_i32 m0, s35, 0x4000
	s_nop 0
	global_load_lds_dwordx4 v[188:189], off
	s_add_i32 m0, s35, 0x6000
	s_nop 0
	global_load_lds_dwordx4 v[190:191], off
	s_add_i32 m0, s35, 0x8000
	s_nop 0
	global_load_lds_dwordx4 v[192:193], off
	s_add_i32 m0, s35, 0xa000
	s_nop 0
	global_load_lds_dwordx4 v[194:195], off
	s_add_i32 m0, s35, 0xc000
	s_nop 0
	global_load_lds_dwordx4 v[196:197], off
	s_add_i32 m0, s35, 0xe000
	s_cmp_lt_i32 s8, 0
	global_load_lds_dwordx4 v[198:199], off
	s_waitcnt vmcnt(4)
	s_barrier
	s_cbranch_scc1 .LBB0_355
	s_waitcnt lgkmcnt(0)
	v_mov_b32_e32 v14, v2
	v_mov_b32_e32 v15, v2
	s_lshl_b32 s8, s8, 2
	v_mov_b32_e32 v0, v2
	v_mov_b32_e32 v1, v2
	v_mov_b32_e32 v3, v2
	v_mov_b32_e32 v4, v2
	v_mov_b32_e32 v5, v2
	v_mov_b32_e32 v6, v2
	v_mov_b32_e32 v7, v2
	v_mov_b32_e32 v8, v2
	v_mov_b32_e32 v9, v2
	v_mov_b32_e32 v10, v2
	v_mov_b32_e32 v11, v2
	v_mov_b32_e32 v12, v2
	v_mov_b32_e32 v13, v2
	v_mov_b64_e32 v[30:31], v[14:15]
	v_mov_b64_e32 v[46:47], v[14:15]
	v_mov_b64_e32 v[62:63], v[14:15]
	v_mov_b64_e32 v[78:79], v[14:15]
	s_add_i32 s38, s8, 4
	s_or_b32 s39, s26, 31
	v_or_b32_e32 v167, s26, v164
	s_mov_b32 s40, 0
	v_mov_b32_e32 v234, 0xf149f2ca
	v_mov_b32_e32 v233, 0
	v_mov_b64_e32 v[210:211], v[208:209]
	v_mov_b64_e32 v[212:213], v[206:207]
	v_mov_b64_e32 v[214:215], v[204:205]
	v_mov_b64_e32 v[216:217], v[202:203]
	v_mov_b64_e32 v[28:29], v[12:13]
	v_mov_b64_e32 v[26:27], v[10:11]
	v_mov_b64_e32 v[24:25], v[8:9]
	v_mov_b64_e32 v[22:23], v[6:7]
	v_mov_b64_e32 v[20:21], v[4:5]
	v_mov_b64_e32 v[18:19], v[2:3]
	v_mov_b64_e32 v[16:17], v[0:1]
	v_mov_b64_e32 v[44:45], v[12:13]
	v_mov_b64_e32 v[42:43], v[10:11]
	v_mov_b64_e32 v[40:41], v[8:9]
	v_mov_b64_e32 v[38:39], v[6:7]
	v_mov_b64_e32 v[36:37], v[4:5]
	v_mov_b64_e32 v[34:35], v[2:3]
	v_mov_b64_e32 v[32:33], v[0:1]
	v_mov_b64_e32 v[60:61], v[12:13]
	v_mov_b64_e32 v[58:59], v[10:11]
	v_mov_b64_e32 v[56:57], v[8:9]
	v_mov_b64_e32 v[54:55], v[6:7]
	v_mov_b64_e32 v[52:53], v[4:5]
	v_mov_b64_e32 v[50:51], v[2:3]
	v_mov_b64_e32 v[48:49], v[0:1]
	v_mov_b64_e32 v[76:77], v[12:13]
	v_mov_b64_e32 v[74:75], v[10:11]
	v_mov_b64_e32 v[72:73], v[8:9]
	v_mov_b64_e32 v[70:71], v[6:7]
	v_mov_b64_e32 v[68:69], v[4:5]
	v_mov_b64_e32 v[66:67], v[2:3]
	v_mov_b64_e32 v[64:65], v[0:1]
	s_mov_b32 s41, 0
	s_mov_b32 s42, 0
	s_waitcnt vmcnt(0)
	v_lshl_add_u32 v218, v166, 1, v230
	ds_read_b128 v[140:143], v218
	ds_read_b128 v[144:147], v218 offset:32
	ds_read_b128 v[148:151], v218 offset:6656
	ds_read_b128 v[152:155], v218 offset:6688
	s_cmp_lt_u32 s34, 0x80
	s_cbranch_scc1 .Lmla_pro_done
	s_add_i32 s31, s35, 0x10000
	s_mov_b32 m0, s31
	s_nop 0
	global_load_lds_dwordx4 v[210:211], off
	s_add_i32 m0, s31, 0x2000
	s_nop 0
	global_load_lds_dwordx4 v[212:213], off
	s_add_i32 m0, s31, 0x4000
	s_nop 0
	global_load_lds_dwordx4 v[214:215], off
	s_add_i32 m0, s31, 0x6000
	s_nop 0
	global_load_lds_dwordx4 v[216:217], off
	v_lshl_add_u64 v[216:217], v[216:217], 0, s[18:19]
	v_lshl_add_u64 v[214:215], v[214:215], 0, s[20:21]
	v_lshl_add_u64 v[212:213], v[212:213], 0, s[2:3]
	v_lshl_add_u64 v[210:211], v[210:211], 0, s[22:23]
	s_barrier

; #define MFMA32(a, b, c) __builtin_amdgcn_mfma_f32_32x32x16_bf16((a), (b), (c), 0, 0, 0)
; #define VFRAG(dst, kk_) do { _Pragma("unroll") for (int mt = 0; mt < 4; ++mt) dst[mt] = *(const LAS bf16x8*)(vb + (32 * mt + r32) * VP + 16 * (kk_) + 8 * hf); } while (0)
; #define KFRAG(da, dc, ks_) do { da = *(const LAS bf16x8*)(kb + r32 * KP + 16 * (ks_) + 8 * hf); dc = *(const LAS bf16x8*)(kb + (32 + r32) * KP + 16 * (ks_) + 8 * hf); } while (0)
; DI void mla_attn_phase(LAS unsigned char* lds, const bf16_t* Qg, const bf16_t* Kg, const bf16_t* Vtg, bf16_t* MIX) {
;     ...
;                     KFRAG(ka0, kc0_, 0); KFRAG(ka1, kc1_, 1);
;                     __builtin_amdgcn_sched_barrier(0);
;                     f32x16 s0, s1;
; #pragma unroll
;                     for (int i = 0; i < 16; ++i) { s0[i] = 0.f; s1[i] = 0.f; }
;                     s0 = MFMA32(ka0, qf[0], s0); s1 = MFMA32(kc0_, qf[0], s1); KFRAG(ka0, kc0_, 2); __builtin_amdgcn_sched_barrier(0);
;                     s0 = MFMA32(ka1, qf[1], s0); s1 = MFMA32(kc1_, qf[1], s1); KFRAG(ka1, kc1_, 3); __builtin_amdgcn_sched_barrier(0);
;                     s0 = MFMA32(ka0, qf[2], s0); s1 = MFMA32(kc0_, qf[2], s1); KFRAG(ka0, kc0_, 4); __builtin_amdgcn_sched_barrier(0);
;                     s0 = MFMA32(ka1, qf[3], s0); s1 = MFMA32(kc1_, qf[3], s1); KFRAG(ka1, kc1_, 5); __builtin_amdgcn_sched_barrier(0);
;                     s0 = MFMA32(ka0, qf[4], s0); s1 = MFMA32(kc0_, qf[4], s1); s0 = MFMA32(ka1, qf[5], s0); s1 = MFMA32(kc1_, qf[5], s1);
;     ...
;                     bf16x8 vfa[4], vfb[4];
;                     VFRAG(vfa, 0); VFRAG(vfb, 1);
.LBB0_361:
	s_cmp_gt_i32 s40, s39
	s_cbranch_scc1 .Lmla_z
	s_lshl_b32 s30, s41, 15
	s_add_i32 s30, s30, 0
	v_lshlrev_b32_e32 v0, 1, v166
	v_add_u32_e32 v1, s30, v0
	v_add_u32_e32 v3, v1, v230
	s_waitcnt lgkmcnt(0)
	v_mfma_f32_32x32x16_bf16 v[80:95], v[140:143], v[112:115], 0
	ds_read_b128 v[4:7], v3 offset:64
	ds_read_b128 v[140:143], v3 offset:6720
	v_mfma_f32_32x32x16_bf16 v[80:95], v[144:147], v[116:119], v[80:95]
	ds_read_b128 v[8:11], v3 offset:96
	ds_read_b128 v[144:147], v3 offset:6752
	s_waitcnt lgkmcnt(0)
	v_mfma_f32_32x32x16_bf16 v[80:95], v[4:7], v[120:123], v[80:95]
	ds_read_b128 v[4:7], v3 offset:128
	ds_read_b128 v[12:15], v3 offset:6784
	v_mfma_f32_32x32x16_bf16 v[80:95], v[8:11], v[124:127], v[80:95]
	ds_read_b128 v[8:11], v3 offset:160
	ds_read_b128 v[236:239], v3 offset:6816
	v_mfma_f32_32x32x16_bf16 v[96:111], v[148:151], v[112:115], 0
	v_add_u32_e32 v1, v1, v232
	v_mfma_f32_32x32x16_bf16 v[96:111], v[152:155], v[116:119], v[96:111]
	v_mfma_f32_32x32x16_bf16 v[96:111], v[140:143], v[120:123], v[96:111]
	v_mfma_f32_32x32x16_bf16 v[96:111], v[144:147], v[124:127], v[96:111]
	ds_read_b128 v[144:147], v1 offset:13312
	ds_read_b128 v[140:143], v1 offset:17920
	s_waitcnt lgkmcnt(2)
	v_mfma_f32_32x32x16_bf16 v[80:95], v[4:7], v[128:131], v[80:95]
	v_mfma_f32_32x32x16_bf16 v[96:111], v[12:15], v[128:131], v[96:111]
	ds_read_b128 v[148:151], v1 offset:22528
	ds_read_b128 v[152:155], v1 offset:27136
	v_add3_u32 v1, s30, v232, v0
	v_mfma_f32_32x32x16_bf16 v[80:95], v[8:11], v[132:135], v[80:95]
	ds_read_b128 v[136:139], v1 offset:13344
	ds_read_b128 v[12:15], v1 offset:17952
	ds_read_b128 v[4:7], v1 offset:22560
	ds_read_b128 v[8:11], v1 offset:27168
	v_mfma_f32_32x32x16_bf16 v[96:111], v[236:239], v[132:135], v[96:111]

; #define KFRAG(da, dc, ks_) do { da = *(const LAS bf16x8*)(kb + r32 * KP + 16 * (ks_) + 8 * hf); dc = *(const LAS bf16x8*)(kb + (32 + r32) * KP + 16 * (ks_) + 8 * hf); } while (0)
; DI void mla_attn_phase(LAS unsigned char* lds, const bf16_t* Qg, const bf16_t* Kg, const bf16_t* Vtg, bf16_t* MIX) {
;     ...
;                     KFRAG(ka0, kc0_, 0); KFRAG(ka1, kc1_, 1);
.Lmla_xb:
	s_barrier
	s_cmp_gt_i32 s40, s39
	s_cbranch_scc1 .LBB0_367
	s_waitcnt lgkmcnt(6)
	v_mfma_f32_32x32x16_bf16 v[64:79], v[144:147], v[80:83], v[64:79]
	v_mfma_f32_32x32x16_bf16 v[48:63], v[140:143], v[80:83], v[48:63]
	s_waitcnt lgkmcnt(0)
	v_mfma_f32_32x32x16_bf16 v[32:47], v[148:151], v[80:83], v[32:47]
	v_mfma_f32_32x32x16_bf16 v[16:31], v[152:155], v[80:83], v[16:31]
	ds_read_b128 v[80:83], v1 offset:13376
	ds_read_b128 v[96:99], v1 offset:17984
	ds_read_b128 v[100:103], v1 offset:22592
	ds_read_b128 v[104:107], v1 offset:27200
	v_mfma_f32_32x32x16_bf16 v[64:79], v[136:139], v[88:91], v[64:79]
	v_mfma_f32_32x32x16_bf16 v[48:63], v[12:15], v[88:91], v[48:63]
	v_mfma_f32_32x32x16_bf16 v[32:47], v[4:7], v[88:91], v[32:47]
	v_mfma_f32_32x32x16_bf16 v[16:31], v[8:11], v[88:91], v[16:31]
	ds_read_b128 v[4:7], v1 offset:13408
	ds_read_b128 v[8:11], v1 offset:18016
	ds_read_b128 v[12:15], v1 offset:22624
	ds_read_b128 v[88:91], v1 offset:27232
	s_add_i32 s30, s41, 1
	s_and_b32 s30, s30, 3
	s_lshl_b32 s30, s30, 15
	v_lshl_add_u32 v218, v166, 1, v230
	v_add_u32_e32 v218, s30, v218
	ds_read_b128 v[140:143], v218
	ds_read_b128 v[144:147], v218 offset:32
	ds_read_b128 v[148:151], v218 offset:6656
	ds_read_b128 v[152:155], v218 offset:6688
	s_waitcnt lgkmcnt(8)
	v_mfma_f32_32x32x16_bf16 v[64:79], v[80:83], v[84:87], v[64:79]
	v_mov_b32_e32 v233, v236
	v_mfma_f32_32x32x16_bf16 v[48:63], v[96:99], v[84:87], v[48:63]
	v_mfma_f32_32x32x16_bf16 v[32:47], v[100:103], v[84:87], v[32:47]
	v_mfma_f32_32x32x16_bf16 v[16:31], v[104:107], v[84:87], v[16:31]
	s_waitcnt lgkmcnt(4)
	v_mfma_f32_32x32x16_bf16 v[64:79], v[4:7], v[92:95], v[64:79]
	v_mfma_f32_32x32x16_bf16 v[48:63], v[8:11], v[92:95], v[48:63]
	v_mfma_f32_32x32x16_bf16 v[32:47], v[12:15], v[92:95], v[32:47]
	v_mfma_f32_32x32x16_bf16 v[16:31], v[88:91], v[92:95], v[16:31]
	s_branch .LBB0_371
